# phase 0: x->bf16 copy and posbias dot loops software-pipelined (4 / 8 iterations of loads in flight)
# speedup vs baseline: 1.0102x; 1.0078x over previous
.LBB0_741:
	s_waitcnt vmcnt(5)
	v_mov_b32_e32 v10, v169
	v_readlane_b32 s2, v254, 32
	s_nop 1
	v_add_u32_e32 v0, s2, v10
	s_mov_b32 s2, 0x400000
	v_cmp_gt_u32_e32 vcc, s2, v0
	s_and_saveexec_b64 s[34:35], vcc
	s_cbranch_execz .LBB0_744
	s_load_dword s2, s[22:23], 0x10
	s_load_dword s8, s[22:23], 0x0
	v_readlane_b32 s40, v253, 2
	v_lshlrev_b64 v[2:3], 5, v[0:1]
	v_readlane_b32 s41, v253, 3
	s_waitcnt lgkmcnt(0)
	s_lshr_b32 s2, s2, 16
	s_cmp_lg_u32 s2, 0
	s_cselect_b64 s[4:5], -1, 0
	s_cmp_lg_u64 s[4:5], 0
	s_addc_u32 s2, s8, 0
	s_lshl_b32 s38, s2, 8
	s_ashr_i32 s39, s38, 31
	v_readlane_b32 s4, v254, 28
	v_readlane_b32 s5, v254, 29
	s_add_u32 s4, s4, s28
	v_readlane_b32 s42, v253, 4
	v_readlane_b32 s43, v253, 5
	s_addc_u32 s5, s5, s29
	v_lshl_add_u64 v[2:3], s[40:41], 0, v[2:3]
	s_lshl_b64 s[28:29], s[38:39], 4
	v_lshl_add_u64 v[4:5], v[0:1], 4, s[4:5]
	s_lshl_b64 s[40:41], s[38:39], 5
	s_mov_b64 s[42:43], 0
	v_mov_b64_e32 v[6:7], v[0:1]
	v_readlane_b32 s44, v253, 6
	v_readlane_b32 s45, v253, 7
	v_readlane_b32 s46, v253, 8
	v_readlane_b32 s47, v253, 9
	v_readlane_b32 s48, v253, 10
	v_readlane_b32 s49, v253, 11
	v_readlane_b32 s50, v253, 12
	v_readlane_b32 s51, v253, 13
	v_readlane_b32 s52, v253, 14
	v_readlane_b32 s53, v253, 15
	v_readlane_b32 s54, v253, 16
	v_readlane_b32 s55, v253, 17
	s_cmp_lg_u32 s38, 0x20000
	s_cbranch_scc1 .LBB0_743
.Lxb4_loop:
	global_load_dwordx4 v[12:15], v[2:3], off offset:16
	global_load_dwordx4 v[16:19], v[2:3], off
	v_lshl_add_u64 v[2:3], v[2:3], 0, s[40:41]
	v_lshl_add_u64 v[6:7], v[6:7], 0, s[38:39]
	global_load_dwordx4 v[20:23], v[2:3], off offset:16
	global_load_dwordx4 v[24:27], v[2:3], off
	v_lshl_add_u64 v[2:3], v[2:3], 0, s[40:41]
	v_lshl_add_u64 v[6:7], v[6:7], 0, s[38:39]
	global_load_dwordx4 v[28:31], v[2:3], off offset:16
	global_load_dwordx4 v[32:35], v[2:3], off
	v_lshl_add_u64 v[2:3], v[2:3], 0, s[40:41]
	v_lshl_add_u64 v[6:7], v[6:7], 0, s[38:39]
	global_load_dwordx4 v[36:39], v[2:3], off offset:16
	global_load_dwordx4 v[40:43], v[2:3], off
	v_lshl_add_u64 v[2:3], v[2:3], 0, s[40:41]
	v_lshl_add_u64 v[6:7], v[6:7], 0, s[38:39]
	s_mov_b64 s[4:5], 0x3fffff
	v_cmp_lt_u64_e32 vcc, s[4:5], v[6:7]
	s_or_b64 s[42:43], vcc, s[42:43]
	s_waitcnt vmcnt(6)
	v_cvt_pk_bf16_f32 v15, v14, v15
	v_cvt_pk_bf16_f32 v14, v12, v13
	v_cvt_pk_bf16_f32 v13, v18, v19
	v_cvt_pk_bf16_f32 v12, v16, v17
	global_store_dwordx4 v[4:5], v[12:15], off
	v_lshl_add_u64 v[4:5], v[4:5], 0, s[28:29]
	s_waitcnt vmcnt(5)
	v_cvt_pk_bf16_f32 v23, v22, v23
	v_cvt_pk_bf16_f32 v22, v20, v21
	v_cvt_pk_bf16_f32 v21, v26, v27
	v_cvt_pk_bf16_f32 v20, v24, v25
	global_store_dwordx4 v[4:5], v[20:23], off
	v_lshl_add_u64 v[4:5], v[4:5], 0, s[28:29]
	s_waitcnt vmcnt(4)
	v_cvt_pk_bf16_f32 v31, v30, v31
	v_cvt_pk_bf16_f32 v30, v28, v29
	v_cvt_pk_bf16_f32 v29, v34, v35
	v_cvt_pk_bf16_f32 v28, v32, v33
	global_store_dwordx4 v[4:5], v[28:31], off
	v_lshl_add_u64 v[4:5], v[4:5], 0, s[28:29]
	s_waitcnt vmcnt(3)
	v_cvt_pk_bf16_f32 v39, v38, v39
	v_cvt_pk_bf16_f32 v38, v36, v37
	v_cvt_pk_bf16_f32 v37, v42, v43
	v_cvt_pk_bf16_f32 v36, v40, v41
	global_store_dwordx4 v[4:5], v[36:39], off
	v_lshl_add_u64 v[4:5], v[4:5], 0, s[28:29]
	s_andn2_b64 exec, exec, s[42:43]
	s_cbranch_execnz .Lxb4_loop
	s_branch .LBB0_744

.LBB0_746:
	s_movk_i32 s2, 0x7bf
	s_mov_b64 s[4:5], 0x8000
	global_load_dword v13, v[6:7], off
	global_load_dword v14, v[8:9], off
	v_lshl_add_u64 v[6:7], v[6:7], 0, s[70:71]
	v_lshl_add_u64 v[8:9], v[8:9], 0, s[4:5]
	global_load_dword v15, v[6:7], off
	global_load_dword v16, v[8:9], off
	v_lshl_add_u64 v[6:7], v[6:7], 0, s[70:71]
	v_lshl_add_u64 v[8:9], v[8:9], 0, s[4:5]
	global_load_dword v17, v[6:7], off
	global_load_dword v18, v[8:9], off
	v_lshl_add_u64 v[6:7], v[6:7], 0, s[70:71]
	v_lshl_add_u64 v[8:9], v[8:9], 0, s[4:5]
	global_load_dword v19, v[6:7], off
	global_load_dword v20, v[8:9], off
	v_lshl_add_u64 v[6:7], v[6:7], 0, s[70:71]
	v_lshl_add_u64 v[8:9], v[8:9], 0, s[4:5]
	global_load_dword v21, v[6:7], off
	global_load_dword v22, v[8:9], off
	v_lshl_add_u64 v[6:7], v[6:7], 0, s[70:71]
	v_lshl_add_u64 v[8:9], v[8:9], 0, s[4:5]
	global_load_dword v23, v[6:7], off
	global_load_dword v24, v[8:9], off
	v_lshl_add_u64 v[6:7], v[6:7], 0, s[70:71]
	v_lshl_add_u64 v[8:9], v[8:9], 0, s[4:5]
	global_load_dword v25, v[6:7], off
	global_load_dword v26, v[8:9], off
	v_lshl_add_u64 v[6:7], v[6:7], 0, s[70:71]
	v_lshl_add_u64 v[8:9], v[8:9], 0, s[4:5]
	global_load_dword v27, v[6:7], off
	global_load_dword v28, v[8:9], off
	v_lshl_add_u64 v[6:7], v[6:7], 0, s[70:71]
	v_lshl_add_u64 v[8:9], v[8:9], 0, s[4:5]
	v_add_u32_e32 v5, 0x200, v5
	v_cmp_lt_u32_e32 vcc, s2, v5
	s_or_b64 s[34:35], vcc, s[34:35]
	s_waitcnt vmcnt(14)
	v_fmac_f32_e32 v12, v13, v14
	s_waitcnt vmcnt(12)
	v_fmac_f32_e32 v12, v15, v16
	s_waitcnt vmcnt(10)
	v_fmac_f32_e32 v12, v17, v18
	s_waitcnt vmcnt(8)
	v_fmac_f32_e32 v12, v19, v20
	s_waitcnt vmcnt(6)
	v_fmac_f32_e32 v12, v21, v22
	s_waitcnt vmcnt(4)
	v_fmac_f32_e32 v12, v23, v24
	s_waitcnt vmcnt(2)
	v_fmac_f32_e32 v12, v25, v26
	s_waitcnt vmcnt(0)
	v_fmac_f32_e32 v12, v27, v28
	s_andn2_b64 exec, exec, s[34:35]
	s_cbranch_execnz .LBB0_746
	s_or_b64 exec, exec, s[34:35]
	v_cmp_lt_i32_e32 vcc, v184, v183
	s_nop 1
	v_cndmask_b32_e32 v5, v182, v184, vcc
	v_lshlrev_b32_e32 v5, 2, v5
	ds_bpermute_b32 v5, v5, v12
	v_cmp_lt_i32_e32 vcc, v185, v183
	s_waitcnt lgkmcnt(0)
	v_add_f32_e32 v5, v12, v5
	v_cndmask_b32_e32 v6, v182, v185, vcc
	v_lshlrev_b32_e32 v6, 2, v6
	ds_bpermute_b32 v6, v6, v5
	s_waitcnt lgkmcnt(0)
	v_add_f32_e32 v5, v5, v6
	v_xor_b32_e32 v6, 8, v182
	v_cmp_lt_i32_e32 vcc, v6, v183
	s_nop 1
	v_cndmask_b32_e32 v6, v182, v6, vcc
	v_lshlrev_b32_e32 v6, 2, v6
	ds_bpermute_b32 v6, v6, v5
	s_waitcnt lgkmcnt(0)
	v_add_f32_e32 v5, v5, v6
	v_xor_b32_e32 v6, 4, v182
	v_cmp_lt_i32_e32 vcc, v6, v183
	s_nop 1
	v_cndmask_b32_e32 v6, v182, v6, vcc
	v_lshlrev_b32_e32 v6, 2, v6
	ds_bpermute_b32 v6, v6, v5
	s_waitcnt lgkmcnt(0)
	v_add_f32_e32 v5, v5, v6
	v_xor_b32_e32 v6, 2, v182
	v_cmp_lt_i32_e32 vcc, v6, v183
	s_nop 1
	v_cndmask_b32_e32 v6, v182, v6, vcc
	v_lshlrev_b32_e32 v6, 2, v6
	ds_bpermute_b32 v6, v6, v5
	s_waitcnt lgkmcnt(0)
	v_add_f32_e32 v5, v5, v6
	v_xor_b32_e32 v6, 1, v182
	v_cmp_lt_i32_e32 vcc, v6, v183
	s_nop 1
	v_cndmask_b32_e32 v6, v182, v6, vcc
	v_lshlrev_b32_e32 v6, 2, v6
	ds_bpermute_b32 v6, v6, v5
	v_cmp_eq_u32_e32 vcc, 0, v11
	s_and_b64 exec, exec, vcc
	s_cbranch_execz .LBB0_749
	v_lshl_or_b32 v4, v4, 7, v3
	v_readlane_b32 s40, v253, 2
	s_waitcnt lgkmcnt(0)
	v_add_f32_e32 v6, v5, v6
	v_ashrrev_i32_e32 v5, 31, v4
	v_readlane_b32 s52, v253, 14
	v_readlane_b32 s53, v253, 15
	v_readlane_b32 s41, v253, 3
	v_readlane_b32 s42, v253, 4
	v_lshl_add_u64 v[4:5], v[4:5], 2, s[52:53]
	global_load_dword v3, v[4:5], off
	v_readlane_b32 s43, v253, 5
	v_readlane_b32 s44, v253, 6
	v_readlane_b32 s45, v253, 7
	v_readlane_b32 s46, v253, 8
	v_readlane_b32 s47, v253, 9
	v_readlane_b32 s48, v253, 10
	v_readlane_b32 s49, v253, 11
	v_readlane_b32 s50, v253, 12
	v_readlane_b32 s51, v253, 13
	v_readlane_b32 s54, v253, 16
	v_readlane_b32 s55, v253, 17
	s_waitcnt vmcnt(0)
	v_add_f32_e32 v6, v6, v3
	v_ashrrev_i32_e32 v3, 31, v2
	v_lshl_add_u64 v[4:5], v[2:3], 2, s[0:1]
	v_add_co_u32_e32 v4, vcc, 0x4190000, v4
	s_nop 1
	v_addc_co_u32_e32 v5, vcc, 0, v5, vcc
	global_store_dword v[4:5], v6, off
